# OIN/EIN 128x128 k-loops: two k-tiles in flight instead of four (prologue requests 2 tiles, in-loop request is tile kt+2, wait vmcnt(4)); FFN1 stays at two in flight
# speedup vs baseline: 1.0099x; 1.0099x over previous
; #define G_TILE(kt_, st_) do { const size_t ko_ = (size_t)(kt_) * 1024; unsigned char* d_ = smem + (st_) * 16384; \
;         _Pragma("unroll") for (int s_ = 0; s_ < 8; ++s_) GLDS16(Abase + (size_t)s_ * ksub + ko_ + voff, d_ + s_ * 1024); \
;         _Pragma("unroll") for (int s_ = 0; s_ < 8; ++s_) GLDS16(Bbase + (size_t)s_ * ksub + ko_ + voff, d_ + 8192 + s_ * 1024); } while (0)
; template <int EPI>
; __device__ __forceinline__ void gemm_tile(const Params& p, int l, const u16* __restrict__ A, int lda, const u16* __restrict__ Bt, int K, int m0, int n0, unsigned char* smem) {
;     ...
;     const int nk = K >> 5;
;     G_TILE(wid, wid);
;     const unsigned char* fa = smem + (wr * 4) * 1024 + fr * 64 + fq * 16;
;     const unsigned char* fb = smem + 8192 + (wc * 4) * 1024 + fr * 64 + fq * 16;
;     int st = 0, stn = 4;
;     if (wid == 0) asm volatile("s_waitcnt vmcnt(0)" ::: "memory");
;     __builtin_amdgcn_s_barrier();
;     asm volatile("" ::: "memory");
;     for (int kt = 0; kt < nk; ++kt) {
;         if (((kt + 1) & 3) == wid && kt + 1 < nk) asm volatile("s_waitcnt vmcnt(0)" ::: "memory");
;         __builtin_amdgcn_s_barrier();
;         asm volatile("" ::: "memory");
;         if ((kt & 3) == wid && kt + 4 < nk) G_TILE(kt + 4, stn);
.Loin_pro:
	s_add_i32 s1, s23, s37
	s_mov_b32 m0, s1
	s_add_i32 s1, s1, 0x400
	global_load_lds_dwordx4 v252, s[30:31]
	s_mov_b32 m0, s1
	s_add_i32 s1, s23, s38
	global_load_lds_dwordx4 v253, s[30:31]
	s_mov_b32 m0, s1
	s_add_i32 s1, s1, 0x400
	global_load_lds_dwordx4 v252, s[28:29]
	s_mov_b32 m0, s1
	s_add_u32 s30, s30, 0x400
	global_load_lds_dwordx4 v253, s[28:29]
	s_addc_u32 s31, s31, 0
	s_add_u32 s28, s28, 0x400
	s_addc_u32 s29, s29, 0
	s_add_i32 s23, s23, 0x4000
	s_cmp_lg_u32 s23, 0x8000
	s_cbranch_scc1 .Loin_pro
	v_ashrrev_i32_e32 v73, 7, v136
	v_and_b32_e32 v72, 15, v136
	v_and_b32_e32 v67, 1, v66
	v_lshlrev_b32_e32 v2, 12, v73
	v_lshlrev_b32_e32 v3, 6, v72
	v_and_b32_e32 v4, 48, v136
	v_and_b32_e32 v5, 8, v136
	v_lshlrev_b32_e32 v5, 2, v5
	v_xor_b32_e32 v4, v4, v5
	v_add3_u32 v75, v2, v3, v4
	v_lshlrev_b32_e32 v2, 12, v67
	v_add3_u32 v74, v2, v3, v4
	s_waitcnt lgkmcnt(0)
	v_mov_b32_e32 v2, 0
	v_mov_b32_e32 v3, v2
	v_mov_b32_e32 v4, v2
	v_mov_b32_e32 v5, v2
	v_mov_b32_e32 v6, v2
	v_mov_b32_e32 v7, v2
	v_mov_b32_e32 v8, v2
	v_mov_b32_e32 v9, v2
	v_mov_b32_e32 v10, v2
	v_mov_b32_e32 v11, v2
	v_mov_b32_e32 v12, v2
	v_mov_b32_e32 v13, v2
	v_mov_b32_e32 v14, v2
	v_mov_b32_e32 v15, v2
	v_mov_b32_e32 v16, v2
	v_mov_b32_e32 v17, v2
	v_mov_b32_e32 v18, v2
	v_mov_b32_e32 v19, v2
	v_mov_b32_e32 v20, v2
	v_mov_b32_e32 v21, v2
	v_mov_b32_e32 v22, v2
	v_mov_b32_e32 v23, v2
	v_mov_b32_e32 v24, v2
	v_mov_b32_e32 v25, v2
	v_mov_b32_e32 v26, v2
	v_mov_b32_e32 v27, v2
	v_mov_b32_e32 v28, v2
	v_mov_b32_e32 v29, v2
	v_mov_b32_e32 v30, v2
	v_mov_b32_e32 v31, v2
	v_mov_b32_e32 v32, v2
	v_mov_b32_e32 v33, v2
	v_mov_b32_e32 v34, v2
	v_mov_b32_e32 v35, v2
	v_mov_b32_e32 v36, v2
	v_mov_b32_e32 v37, v2
	v_mov_b32_e32 v38, v2
	v_mov_b32_e32 v39, v2
	v_mov_b32_e32 v40, v2
	v_mov_b32_e32 v41, v2
	v_mov_b32_e32 v42, v2
	v_mov_b32_e32 v43, v2
	v_mov_b32_e32 v44, v2
	v_mov_b32_e32 v45, v2
	v_mov_b32_e32 v46, v2
	v_mov_b32_e32 v47, v2
	v_mov_b32_e32 v48, v2
	v_mov_b32_e32 v49, v2
	v_mov_b32_e32 v50, v2
	v_mov_b32_e32 v51, v2
	v_mov_b32_e32 v52, v2
	v_mov_b32_e32 v53, v2
	v_mov_b32_e32 v54, v2
	v_mov_b32_e32 v55, v2
	v_mov_b32_e32 v56, v2
	v_mov_b32_e32 v57, v2
	v_mov_b32_e32 v58, v2
	v_mov_b32_e32 v59, v2
	v_mov_b32_e32 v60, v2
	v_mov_b32_e32 v61, v2
	v_mov_b32_e32 v62, v2
	v_mov_b32_e32 v63, v2
	v_mov_b32_e32 v64, v2
	v_mov_b32_e32 v65, v2
	s_mov_b64 s[46:47], 0x6adc100
	s_mov_b64 s[18:19], 0x6ae4100
	s_mov_b64 s[44:45], 0x6aec100
	s_mov_b32 s36, 0
	s_mov_b32 s0, 0
	v_add_u32_e32 v88, s0, v75
	v_add_u32_e32 v104, s0, v74
	s_branch .Loin_head
.Loin_head:
	s_waitcnt vmcnt(4)
.Loin_bar:
	s_barrier
	ds_read_b128 v[92:95], v104 offset:8192
	ds_read_b128 v[96:99], v104 offset:9216
	ds_read_b128 v[100:103], v104 offset:10240
	ds_read_b128 v[104:107], v104 offset:11264
	ds_read_b128 v[76:79], v88
	ds_read_b128 v[80:83], v88 offset:1024
	ds_read_b128 v[84:87], v88 offset:2048
	ds_read_b128 v[88:91], v88 offset:3072
	s_cmp_lt_u32 s36, 30
	s_cbranch_scc0 .Loin_mm
	s_add_i32 s1, s23, s37
	s_mov_b32 m0, s1
	s_add_i32 s1, s1, 0x400
	global_load_lds_dwordx4 v252, s[30:31]
	s_mov_b32 m0, s1
	s_add_i32 s1, s23, s38
	global_load_lds_dwordx4 v253, s[30:31]
	s_mov_b32 m0, s1
	s_add_i32 s1, s1, 0x400
	global_load_lds_dwordx4 v252, s[28:29]
	s_mov_b32 m0, s1
	s_add_u32 s30, s30, 0x400
	global_load_lds_dwordx4 v253, s[28:29]
	s_addc_u32 s31, s31, 0
	s_add_u32 s28, s28, 0x400
	s_addc_u32 s29, s29, 0
	s_add_i32 s23, s23, 0x4000
	s_cmp_eq_u32 s23, 0x14000
	s_cselect_b32 s23, 0, s23

; #define G_TILE(kt_, st_) do { const size_t ko_ = (size_t)(kt_) * 1024; unsigned char* d_ = smem + (st_) * 16384; \
;         _Pragma("unroll") for (int s_ = 0; s_ < 8; ++s_) GLDS16(Abase + (size_t)s_ * ksub + ko_ + voff, d_ + s_ * 1024); \
;         _Pragma("unroll") for (int s_ = 0; s_ < 8; ++s_) GLDS16(Bbase + (size_t)s_ * ksub + ko_ + voff, d_ + 8192 + s_ * 1024); } while (0)
; template <int EPI>
; __device__ __forceinline__ void gemm_tile(const Params& p, int l, const u16* __restrict__ A, int lda, const u16* __restrict__ Bt, int K, int m0, int n0, unsigned char* smem) {
;     ...
;     const int nk = K >> 5;
;     G_TILE(wid, wid);
;     const unsigned char* fa = smem + (wr * 4) * 1024 + fr * 64 + fq * 16;
;     const unsigned char* fb = smem + 8192 + (wc * 4) * 1024 + fr * 64 + fq * 16;
;     int st = 0, stn = 4;
.Lein_pro:
	s_add_i32 s1, s23, s37
	s_mov_b32 m0, s1
	s_add_i32 s1, s1, 0x400
	global_load_lds_dwordx4 v252, s[30:31]
	s_mov_b32 m0, s1
	s_add_i32 s1, s23, s38
	global_load_lds_dwordx4 v253, s[30:31]
	s_mov_b32 m0, s1
	s_add_i32 s1, s1, 0x400
	global_load_lds_dwordx4 v252, s[28:29]
	s_mov_b32 m0, s1
	s_add_u32 s30, s30, 0x400
	global_load_lds_dwordx4 v253, s[28:29]
	s_addc_u32 s31, s31, 0
	s_add_u32 s28, s28, 0x400
	s_addc_u32 s29, s29, 0
	s_add_i32 s23, s23, 0x4000
	s_cmp_lg_u32 s23, 0x8000
	s_cbranch_scc1 .Lein_pro
	v_ashrrev_i32_e32 v73, 7, v110
	v_and_b32_e32 v72, 15, v110
	v_and_b32_e32 v67, 1, v66
	v_lshlrev_b32_e32 v2, 12, v73
	v_lshlrev_b32_e32 v3, 6, v72
	v_and_b32_e32 v4, 48, v110
	v_and_b32_e32 v5, 8, v110
	v_lshlrev_b32_e32 v5, 2, v5
	v_xor_b32_e32 v4, v4, v5
	v_add3_u32 v75, v2, v3, v4
	v_lshlrev_b32_e32 v2, 12, v67
	v_add3_u32 v74, v2, v3, v4
	s_waitcnt lgkmcnt(0)
	v_mov_b32_e32 v2, 0
	v_mov_b32_e32 v3, v2
	v_mov_b32_e32 v4, v2
	v_mov_b32_e32 v5, v2
	v_mov_b32_e32 v6, v2
	v_mov_b32_e32 v7, v2
	v_mov_b32_e32 v8, v2
	v_mov_b32_e32 v9, v2
	v_mov_b32_e32 v10, v2
	v_mov_b32_e32 v11, v2
	v_mov_b32_e32 v12, v2
	v_mov_b32_e32 v13, v2
	v_mov_b32_e32 v14, v2
	v_mov_b32_e32 v15, v2
	v_mov_b32_e32 v16, v2
	v_mov_b32_e32 v17, v2
	v_mov_b32_e32 v18, v2
	v_mov_b32_e32 v19, v2
	v_mov_b32_e32 v20, v2
	v_mov_b32_e32 v21, v2
	v_mov_b32_e32 v22, v2
	v_mov_b32_e32 v23, v2
	v_mov_b32_e32 v24, v2
	v_mov_b32_e32 v25, v2
	v_mov_b32_e32 v26, v2
	v_mov_b32_e32 v27, v2
	v_mov_b32_e32 v28, v2
	v_mov_b32_e32 v29, v2
	v_mov_b32_e32 v30, v2
	v_mov_b32_e32 v31, v2
	v_mov_b32_e32 v32, v2
	v_mov_b32_e32 v33, v2
	v_mov_b32_e32 v34, v2
	v_mov_b32_e32 v35, v2
	v_mov_b32_e32 v36, v2
	v_mov_b32_e32 v37, v2
	v_mov_b32_e32 v38, v2
	v_mov_b32_e32 v39, v2
	v_mov_b32_e32 v40, v2
	v_mov_b32_e32 v41, v2
	v_mov_b32_e32 v42, v2
	v_mov_b32_e32 v43, v2
	v_mov_b32_e32 v44, v2
	v_mov_b32_e32 v45, v2
	v_mov_b32_e32 v46, v2
	v_mov_b32_e32 v47, v2
	v_mov_b32_e32 v48, v2
	v_mov_b32_e32 v49, v2
	v_mov_b32_e32 v50, v2
	v_mov_b32_e32 v51, v2
	v_mov_b32_e32 v52, v2
	v_mov_b32_e32 v53, v2
	v_mov_b32_e32 v54, v2
	v_mov_b32_e32 v55, v2
	v_mov_b32_e32 v56, v2
	v_mov_b32_e32 v57, v2
	v_mov_b32_e32 v58, v2
	v_mov_b32_e32 v59, v2
	v_mov_b32_e32 v60, v2
	v_mov_b32_e32 v61, v2
	v_mov_b32_e32 v62, v2
	v_mov_b32_e32 v63, v2
	v_mov_b32_e32 v64, v2
	v_mov_b32_e32 v65, v2
	s_mov_b64 s[18:19], 0x6ae4100
	s_mov_b64 s[40:41], 0x6aec100
	s_mov_b32 s36, 0
	s_mov_b32 s0, 0
	v_add_u32_e32 v88, s0, v75
	v_add_u32_e32 v104, s0, v74
	s_branch .Lein_head
